# K-loop loop-edge edit: pointer/counter bumps moved above the loop-back barrier, phase-1 ds_reads issued ahead of the last-tile select chain; otherwise v048
# baseline (speedup 1.0000x reference)
.LBB0_836:
	v_add_u32_e32 v2, 0x10000, v252
	ds_read_b128 v[144:147], v2
	ds_read_b128 v[148:151], v2 offset:1024
	ds_read_b128 v[152:155], v2 offset:2048
	ds_read_b128 v[156:159], v2 offset:3072
	v_add_u32_e32 v2, 0x14000, v252
	ds_read_b128 v[160:163], v2
	ds_read_b128 v[164:167], v2 offset:1024
	ds_read_b128 v[168:171], v2 offset:2048
	ds_read_b128 v[172:175], v2 offset:3072
	s_add_u32 s19, s90, s12
	s_addc_u32 s20, s91, s13
	s_and_b64 s[16:17], s[14:15], exec
	s_cselect_b32 s17, s45, s20
	s_cselect_b32 s16, s44, s19
	s_add_u32 s19, s52, s12
	s_addc_u32 s20, s53, s13
	s_lshl_b64 s[24:25], s[40:41], 7
	s_and_b64 s[14:15], s[14:15], exec
	s_cselect_b32 s15, s93, s20
	s_cselect_b32 s14, s92, s19
	s_cselect_b32 s20, s25, s7
	s_cselect_b32 s21, s24, s6
	s_add_i32 s24, 0, 0x10000
	s_add_i32 s25, 0, 0x14000
	s_mov_b32 s19, s41
	v_lshl_add_u64 v[236:237], s[90:91], 0, v[134:135]
	s_add_i32 m0, s78, 0xc000
	ds_read_b128 v[176:179], v229
	ds_read_b128 v[180:183], v229 offset:1024
	ds_read_b128 v[184:187], v229 offset:2048
	ds_read_b128 v[204:207], v229 offset:3072
	ds_read_b128 v[208:211], v229 offset:4096
	ds_read_b128 v[212:215], v229 offset:5120
	ds_read_b128 v[224:227], v229 offset:6144
	ds_read_b128 v[216:219], v229 offset:7168
	global_load_lds_dwordx4 v[236:237], off
	v_lshl_add_u64 v[236:237], s[90:91], 0, v[4:5]
	s_add_i32 m0, s78, 0xe000
	s_nop 0
	global_load_lds_dwordx4 v[236:237], off
	s_waitcnt vmcnt(8)
	s_waitcnt lgkmcnt(0)
	s_barrier
	s_waitcnt lgkmcnt(0)
	v_mfma_f32_16x16x32_bf16 v[126:129], v[144:147], v[176:179], v[126:129]
	v_mfma_f32_16x16x32_bf16 v[130:133], v[152:155], v[176:179], v[130:133]
	v_mfma_f32_16x16x32_bf16 v[118:121], v[144:147], v[184:187], v[118:121]
	v_mfma_f32_16x16x32_bf16 v[122:125], v[152:155], v[184:187], v[122:125]
	v_mfma_f32_16x16x32_bf16 v[110:113], v[144:147], v[208:211], v[110:113]
	v_mfma_f32_16x16x32_bf16 v[114:117], v[152:155], v[208:211], v[114:117]
	v_mfma_f32_16x16x32_bf16 v[102:105], v[144:147], v[224:227], v[102:105]
	v_mfma_f32_16x16x32_bf16 v[106:109], v[152:155], v[224:227], v[106:109]
	v_mfma_f32_16x16x32_bf16 v[126:129], v[148:151], v[180:183], v[126:129]
	v_mfma_f32_16x16x32_bf16 v[130:133], v[156:159], v[180:183], v[130:133]
	v_mfma_f32_16x16x32_bf16 v[118:121], v[148:151], v[204:207], v[118:121]
	v_mfma_f32_16x16x32_bf16 v[122:125], v[156:159], v[204:207], v[122:125]
	v_mfma_f32_16x16x32_bf16 v[110:113], v[148:151], v[212:215], v[110:113]
	v_mfma_f32_16x16x32_bf16 v[114:117], v[156:159], v[212:215], v[114:117]
	v_mfma_f32_16x16x32_bf16 v[102:105], v[148:151], v[216:219], v[102:105]
	v_mfma_f32_16x16x32_bf16 v[106:109], v[156:159], v[216:219], v[106:109]
	v_mfma_f32_16x16x32_bf16 v[94:97], v[160:163], v[176:179], v[94:97]
	v_mfma_f32_16x16x32_bf16 v[98:101], v[168:171], v[176:179], v[98:101]
	v_mfma_f32_16x16x32_bf16 v[86:89], v[160:163], v[184:187], v[86:89]
	v_mfma_f32_16x16x32_bf16 v[90:93], v[168:171], v[184:187], v[90:93]
	v_mfma_f32_16x16x32_bf16 v[78:81], v[160:163], v[208:211], v[78:81]
	v_mfma_f32_16x16x32_bf16 v[82:85], v[168:171], v[208:211], v[82:85]
	v_mfma_f32_16x16x32_bf16 v[70:73], v[160:163], v[224:227], v[70:73]
	v_mfma_f32_16x16x32_bf16 v[74:77], v[168:171], v[224:227], v[74:77]
	v_mfma_f32_16x16x32_bf16 v[94:97], v[164:167], v[180:183], v[94:97]
	v_mfma_f32_16x16x32_bf16 v[98:101], v[172:175], v[180:183], v[98:101]
	v_mfma_f32_16x16x32_bf16 v[86:89], v[164:167], v[204:207], v[86:89]
	v_mfma_f32_16x16x32_bf16 v[90:93], v[172:175], v[204:207], v[90:93]
	v_mfma_f32_16x16x32_bf16 v[78:81], v[164:167], v[212:215], v[78:81]
	v_mfma_f32_16x16x32_bf16 v[82:85], v[172:175], v[212:215], v[82:85]
	v_mfma_f32_16x16x32_bf16 v[70:73], v[164:167], v[216:219], v[70:73]
	v_mfma_f32_16x16x32_bf16 v[74:77], v[172:175], v[216:219], v[74:77]
	s_barrier
	s_add_i32 s24, s24, s5
	s_mov_b32 m0, s24
	ds_read_b128 v[176:179], v229 offset:16384
	ds_read_b128 v[180:183], v229 offset:17408
	ds_read_b128 v[184:187], v229 offset:18432
	ds_read_b128 v[204:207], v229 offset:19456
	ds_read_b128 v[208:211], v229 offset:20480
	ds_read_b128 v[212:215], v229 offset:21504
	ds_read_b128 v[216:219], v229 offset:22528
	ds_read_b128 v[224:227], v229 offset:23552
	v_mov_b32_e32 v143, v3
	global_load_lds_dwordx4 v142, s[14:15]
	v_mov_b32_e32 v141, v3
	s_add_i32 m0, s24, 0x2000
	s_lshl_b64 s[18:19], s[18:19], 7
	v_lshl_add_u64 v[236:237], s[14:15], 0, v[142:143]
	v_lshl_add_u64 v[222:223], s[14:15], 0, v[140:141]
	global_load_lds_dwordx4 v140, s[14:15]
	s_add_u32 s14, s14, s18
	s_addc_u32 s15, s15, s19
	s_add_i32 s18, s25, s5
	s_mov_b32 m0, s18
	v_lshl_add_u64 v[250:251], s[16:17], 0, v[138:139]
	global_load_lds_dwordx4 v142, s[14:15]
	s_add_i32 m0, s18, 0x2000
	v_lshl_add_u64 v[232:233], s[16:17], 0, v[136:137]
	global_load_lds_dwordx4 v140, s[14:15]
	s_mov_b32 m0, s78
	v_lshl_add_u64 v[244:245], s[14:15], 0, v[142:143]
	global_load_lds_dwordx4 v[250:251], off
	s_mov_b32 m0, s87
	v_lshl_add_u64 v[246:247], s[14:15], 0, v[140:141]
	global_load_lds_dwordx4 v[232:233], off
	s_waitcnt vmcnt(8)
	s_waitcnt lgkmcnt(0)
	s_barrier
	s_waitcnt lgkmcnt(0)
	v_mfma_f32_16x16x32_bf16 v[46:49], v[144:147], v[176:179], v[46:49]
	v_mfma_f32_16x16x32_bf16 v[50:53], v[152:155], v[176:179], v[50:53]
	v_mfma_f32_16x16x32_bf16 v[38:41], v[144:147], v[184:187], v[38:41]
	v_mfma_f32_16x16x32_bf16 v[42:45], v[152:155], v[184:187], v[42:45]
	v_mfma_f32_16x16x32_bf16 v[30:33], v[144:147], v[208:211], v[30:33]
	v_mfma_f32_16x16x32_bf16 v[34:37], v[152:155], v[208:211], v[34:37]
	v_mfma_f32_16x16x32_bf16 v[22:25], v[144:147], v[216:219], v[22:25]
	v_mfma_f32_16x16x32_bf16 v[26:29], v[152:155], v[216:219], v[26:29]
	v_mfma_f32_16x16x32_bf16 v[46:49], v[148:151], v[180:183], v[46:49]
	v_mfma_f32_16x16x32_bf16 v[50:53], v[156:159], v[180:183], v[50:53]
	v_mfma_f32_16x16x32_bf16 v[38:41], v[148:151], v[204:207], v[38:41]
	v_mfma_f32_16x16x32_bf16 v[42:45], v[156:159], v[204:207], v[42:45]
	v_mfma_f32_16x16x32_bf16 v[30:33], v[148:151], v[212:215], v[30:33]
	v_mfma_f32_16x16x32_bf16 v[34:37], v[156:159], v[212:215], v[34:37]
	v_mfma_f32_16x16x32_bf16 v[22:25], v[148:151], v[224:227], v[22:25]
	v_mfma_f32_16x16x32_bf16 v[26:29], v[156:159], v[224:227], v[26:29]
	v_mfma_f32_16x16x32_bf16 v[14:17], v[160:163], v[176:179], v[14:17]
	v_mfma_f32_16x16x32_bf16 v[18:21], v[168:171], v[176:179], v[18:21]
	v_mfma_f32_16x16x32_bf16 v[6:9], v[160:163], v[184:187], v[6:9]
	v_mfma_f32_16x16x32_bf16 v[10:13], v[168:171], v[184:187], v[10:13]
	v_mfma_f32_16x16x32_bf16 v[54:57], v[160:163], v[208:211], v[54:57]
	v_mfma_f32_16x16x32_bf16 v[62:65], v[168:171], v[208:211], v[62:65]
	v_mfma_f32_16x16x32_bf16 v[58:61], v[160:163], v[216:219], v[58:61]
	v_mfma_f32_16x16x32_bf16 v[66:69], v[168:171], v[216:219], v[66:69]
	v_mfma_f32_16x16x32_bf16 v[14:17], v[164:167], v[180:183], v[14:17]
	v_mfma_f32_16x16x32_bf16 v[18:21], v[172:175], v[180:183], v[18:21]
	v_mfma_f32_16x16x32_bf16 v[6:9], v[164:167], v[204:207], v[6:9]
	v_mfma_f32_16x16x32_bf16 v[10:13], v[172:175], v[204:207], v[10:13]
	v_mfma_f32_16x16x32_bf16 v[54:57], v[164:167], v[212:215], v[54:57]
	v_mfma_f32_16x16x32_bf16 v[62:65], v[172:175], v[212:215], v[62:65]
	v_mfma_f32_16x16x32_bf16 v[58:61], v[164:167], v[224:227], v[58:61]
	v_mfma_f32_16x16x32_bf16 v[66:69], v[172:175], v[224:227], v[66:69]
	s_barrier
	s_add_i32 s18, 0, 0x18000
	v_add_u32_e32 v2, s18, v252
	s_add_i32 s19, 0, 0x1c000
	ds_read_b128 v[140:143], v2
	ds_read_b128 v[144:147], v2 offset:1024
	ds_read_b128 v[148:151], v2 offset:2048
	ds_read_b128 v[152:155], v2 offset:3072
	v_add_u32_e32 v2, s19, v252
	ds_read_b128 v[156:159], v2
	ds_read_b128 v[160:163], v2 offset:1024
	ds_read_b128 v[164:167], v2 offset:2048
	ds_read_b128 v[168:171], v2 offset:3072
	s_add_u32 s14, s16, s21
	s_addc_u32 s15, s17, s20
	s_mov_b32 m0, s79
	v_lshl_add_u64 v[138:139], s[14:15], 0, v[138:139]
	ds_read_b128 v[172:175], v229 offset:32768
	ds_read_b128 v[176:179], v229 offset:33792
	ds_read_b128 v[180:183], v229 offset:34816
	ds_read_b128 v[184:187], v229 offset:35840
	ds_read_b128 v[204:207], v229 offset:36864
	ds_read_b128 v[208:211], v229 offset:37888
	ds_read_b128 v[212:215], v229 offset:38912
	ds_read_b128 v[216:219], v229 offset:39936
	global_load_lds_dwordx4 v[138:139], off
	v_lshl_add_u64 v[136:137], s[14:15], 0, v[136:137]
	s_mov_b32 m0, s34
	s_nop 0
	global_load_lds_dwordx4 v[136:137], off
	s_waitcnt vmcnt(8)
	s_waitcnt lgkmcnt(0)
	s_barrier
	s_waitcnt lgkmcnt(0)
	v_mfma_f32_16x16x32_bf16 v[126:129], v[140:143], v[172:175], v[126:129]
	v_mfma_f32_16x16x32_bf16 v[130:133], v[148:151], v[172:175], v[130:133]
	v_mfma_f32_16x16x32_bf16 v[118:121], v[140:143], v[180:183], v[118:121]
	v_mfma_f32_16x16x32_bf16 v[122:125], v[148:151], v[180:183], v[122:125]
	v_mfma_f32_16x16x32_bf16 v[110:113], v[140:143], v[204:207], v[110:113]
	v_mfma_f32_16x16x32_bf16 v[114:117], v[148:151], v[204:207], v[114:117]
	v_mfma_f32_16x16x32_bf16 v[102:105], v[140:143], v[212:215], v[102:105]
	v_mfma_f32_16x16x32_bf16 v[106:109], v[148:151], v[212:215], v[106:109]
	v_mfma_f32_16x16x32_bf16 v[126:129], v[144:147], v[176:179], v[126:129]
	v_mfma_f32_16x16x32_bf16 v[130:133], v[152:155], v[176:179], v[130:133]
	v_mfma_f32_16x16x32_bf16 v[118:121], v[144:147], v[184:187], v[118:121]
	v_mfma_f32_16x16x32_bf16 v[122:125], v[152:155], v[184:187], v[122:125]
	v_mfma_f32_16x16x32_bf16 v[110:113], v[144:147], v[208:211], v[110:113]
	v_mfma_f32_16x16x32_bf16 v[114:117], v[152:155], v[208:211], v[114:117]
	v_mfma_f32_16x16x32_bf16 v[102:105], v[144:147], v[216:219], v[102:105]
	v_mfma_f32_16x16x32_bf16 v[106:109], v[152:155], v[216:219], v[106:109]
	v_mfma_f32_16x16x32_bf16 v[94:97], v[156:159], v[172:175], v[94:97]
	v_mfma_f32_16x16x32_bf16 v[98:101], v[164:167], v[172:175], v[98:101]
	v_mfma_f32_16x16x32_bf16 v[86:89], v[156:159], v[180:183], v[86:89]
	v_mfma_f32_16x16x32_bf16 v[90:93], v[164:167], v[180:183], v[90:93]
	v_mfma_f32_16x16x32_bf16 v[78:81], v[156:159], v[204:207], v[78:81]
	v_mfma_f32_16x16x32_bf16 v[82:85], v[164:167], v[204:207], v[82:85]
	v_mfma_f32_16x16x32_bf16 v[70:73], v[156:159], v[212:215], v[70:73]
	v_mfma_f32_16x16x32_bf16 v[74:77], v[164:167], v[212:215], v[74:77]
	v_mfma_f32_16x16x32_bf16 v[94:97], v[160:163], v[176:179], v[94:97]
	v_mfma_f32_16x16x32_bf16 v[98:101], v[168:171], v[176:179], v[98:101]
	v_mfma_f32_16x16x32_bf16 v[86:89], v[160:163], v[184:187], v[86:89]
	v_mfma_f32_16x16x32_bf16 v[90:93], v[168:171], v[184:187], v[90:93]
	v_mfma_f32_16x16x32_bf16 v[78:81], v[160:163], v[208:211], v[78:81]
	v_mfma_f32_16x16x32_bf16 v[82:85], v[168:171], v[208:211], v[82:85]
	v_mfma_f32_16x16x32_bf16 v[70:73], v[160:163], v[216:219], v[70:73]
	v_mfma_f32_16x16x32_bf16 v[74:77], v[168:171], v[216:219], v[74:77]
	s_barrier
	s_add_i32 s14, s18, s5
	v_lshl_add_u64 v[216:217], v[236:237], 0, s[60:61]
	s_mov_b32 m0, s14
	ds_read_b128 v[136:139], v229 offset:49152
	ds_read_b128 v[172:175], v229 offset:50176
	ds_read_b128 v[176:179], v229 offset:51200
	ds_read_b128 v[180:183], v229 offset:52224
	ds_read_b128 v[184:187], v229 offset:53248
	ds_read_b128 v[204:207], v229 offset:54272
	ds_read_b128 v[208:211], v229 offset:55296
	ds_read_b128 v[212:215], v229 offset:56320
	global_load_lds_dwordx4 v[216:217], off
	v_lshl_add_u64 v[216:217], v[222:223], 0, s[60:61]
	s_add_i32 m0, s14, 0x2000
	s_add_i32 s14, s19, s5
	global_load_lds_dwordx4 v[216:217], off
	v_lshl_add_u64 v[216:217], v[244:245], 0, s[60:61]
	s_mov_b32 m0, s14
	s_nop 0
	global_load_lds_dwordx4 v[216:217], off
	v_lshl_add_u64 v[216:217], v[246:247], 0, s[60:61]
	s_add_i32 m0, s14, 0x2000
	s_nop 0
	global_load_lds_dwordx4 v[216:217], off
	v_lshl_add_u64 v[216:217], v[250:251], 0, s[60:61]
	s_mov_b32 m0, s35
	s_nop 0
	global_load_lds_dwordx4 v[216:217], off
	v_lshl_add_u64 v[216:217], v[232:233], 0, s[60:61]
	s_mov_b32 m0, s46
	s_nop 0
	global_load_lds_dwordx4 v[216:217], off
	s_waitcnt vmcnt(8)
	s_waitcnt lgkmcnt(0)
	s_barrier
	s_waitcnt lgkmcnt(0)
	v_mfma_f32_16x16x32_bf16 v[46:49], v[140:143], v[136:139], v[46:49]
	v_mfma_f32_16x16x32_bf16 v[50:53], v[148:151], v[136:139], v[50:53]
	v_mfma_f32_16x16x32_bf16 v[38:41], v[140:143], v[176:179], v[38:41]
	v_mfma_f32_16x16x32_bf16 v[42:45], v[148:151], v[176:179], v[42:45]
	v_mfma_f32_16x16x32_bf16 v[30:33], v[140:143], v[184:187], v[30:33]
	v_mfma_f32_16x16x32_bf16 v[34:37], v[148:151], v[184:187], v[34:37]
	v_mfma_f32_16x16x32_bf16 v[22:25], v[140:143], v[208:211], v[22:25]
	v_mfma_f32_16x16x32_bf16 v[26:29], v[148:151], v[208:211], v[26:29]
	v_mfma_f32_16x16x32_bf16 v[46:49], v[144:147], v[172:175], v[46:49]
	v_mfma_f32_16x16x32_bf16 v[50:53], v[152:155], v[172:175], v[50:53]
	v_mfma_f32_16x16x32_bf16 v[38:41], v[144:147], v[180:183], v[38:41]
	v_mfma_f32_16x16x32_bf16 v[42:45], v[152:155], v[180:183], v[42:45]
	v_mfma_f32_16x16x32_bf16 v[30:33], v[144:147], v[204:207], v[30:33]
	v_mfma_f32_16x16x32_bf16 v[34:37], v[152:155], v[204:207], v[34:37]
	v_mfma_f32_16x16x32_bf16 v[22:25], v[144:147], v[212:215], v[22:25]
	v_mfma_f32_16x16x32_bf16 v[26:29], v[152:155], v[212:215], v[26:29]
	v_mfma_f32_16x16x32_bf16 v[14:17], v[156:159], v[136:139], v[14:17]
	v_mfma_f32_16x16x32_bf16 v[18:21], v[164:167], v[136:139], v[18:21]
	v_mfma_f32_16x16x32_bf16 v[6:9], v[156:159], v[176:179], v[6:9]
	v_mfma_f32_16x16x32_bf16 v[10:13], v[164:167], v[176:179], v[10:13]
	v_mfma_f32_16x16x32_bf16 v[54:57], v[156:159], v[184:187], v[54:57]
	v_mfma_f32_16x16x32_bf16 v[62:65], v[164:167], v[184:187], v[62:65]
	v_mfma_f32_16x16x32_bf16 v[58:61], v[156:159], v[208:211], v[58:61]
	v_mfma_f32_16x16x32_bf16 v[66:69], v[164:167], v[208:211], v[66:69]
	v_mfma_f32_16x16x32_bf16 v[14:17], v[160:163], v[172:175], v[14:17]
	v_mfma_f32_16x16x32_bf16 v[18:21], v[168:171], v[172:175], v[18:21]
	v_mfma_f32_16x16x32_bf16 v[6:9], v[160:163], v[180:183], v[6:9]
	v_mfma_f32_16x16x32_bf16 v[10:13], v[168:171], v[180:183], v[10:13]
	v_mfma_f32_16x16x32_bf16 v[54:57], v[160:163], v[204:207], v[54:57]
	v_mfma_f32_16x16x32_bf16 v[62:65], v[168:171], v[204:207], v[62:65]
	v_mfma_f32_16x16x32_bf16 v[58:61], v[160:163], v[212:215], v[58:61]
	v_mfma_f32_16x16x32_bf16 v[66:69], v[168:171], v[212:215], v[66:69]
	s_add_i32 s14, s63, 2
	s_add_u32 s12, s12, 0x100
	s_addc_u32 s13, s13, 0
	v_lshl_add_u64 v[4:5], v[4:5], 0, s[68:69]
	v_lshl_add_u64 v[134:135], v[134:135], 0, s[68:69]
	s_cmp_ge_i32 s63, s47
	s_barrier
	s_cbranch_scc1 .LBB0_857
	s_mov_b32 s63, s14
	s_branch .LBB0_813
